# PAPR: second-round tile pairs split across two workgroups (PA on WG c, PR on WG c+32, T handed over by release/acquire flag); f2d transposes on the remaining 192 WGs
# baseline (speedup 1.0000x reference)
.LBB0_1396:
	s_waitcnt vmcnt(0)
	s_barrier
	s_cmp_lg_u32 s94, 0x100
	s_cbranch_scc1 .Lpapr_noflag
	s_cmp_ge_u32 s34, 32
	s_cbranch_scc1 .Lpapr_noflag
	v_cmp_eq_u32_e32 vcc, 0, v128
	s_and_saveexec_b64 s[84:85], vcc
	s_cbranch_execz .Lpapr_flagdone
	buffer_wbl2 sc1
	s_waitcnt vmcnt(0)
	s_lshl_b32 s86, s34, 2
	v_mov_b32_e32 v252, s86
	v_mov_b32_e32 v253, 1
	global_atomic_add v252, v253, s[50:51]
.Lpapr_flagdone:
	s_or_b64 exec, exec, s[84:85]
.Lpapr_noflag:
.LBB0_1397:
	s_add_u32 s10, s50, 0x7404000
	v_mov_b32_e32 v9, v128
	s_addc_u32 s11, s51, 0
	s_andn2_b64 vcc, exec, s[12:13]
	v_readfirstlane_b32 s4, v9
	s_cbranch_vccnz .LBB0_1413
	v_lshlrev_b32_e32 v0, 4, v9
	v_add_u32_e32 v1, 0x2000, v0
	s_waitcnt vmcnt(0)
	v_ashrrev_i32_e32 v2, 31, v1
	v_lshrrev_b32_e32 v2, 22, v2
	v_add_u32_e32 v2, v1, v2
	v_ashrrev_i32_e32 v8, 10, v2
	v_mul_i32_i24_e32 v2, 0x400, v8
	v_sub_u32_e32 v1, v1, v2
	v_lshrrev_b32_e32 v2, 4, v1
	v_bitop3_b32 v1, v2, v1, 32 bitop3:0x6c
	v_ashrrev_i32_e32 v2, 31, v1
	v_lshrrev_b32_e32 v2, 26, v2
	v_add_u32_e32 v2, v1, v2
	v_lshlrev_b32_e32 v3, 3, v8
	v_ashrrev_i32_e32 v10, 6, v2
	v_and_b32_e32 v3, -16, v3
	v_add_u32_e32 v3, v10, v3
	v_and_b32_e32 v4, 3, v10
	s_mov_b32 s12, 0xfffe0
	v_lshrrev_b32_e32 v5, 2, v3
	v_lshlrev_b32_e32 v6, 1, v3
	v_and_b32_e32 v2, 0xc0, v2
	v_and_or_b32 v4, v3, s12, v4
	v_and_b32_e32 v5, 4, v5
	v_and_b32_e32 v6, 24, v6
	v_sub_u32_e32 v1, v1, v2
	v_mov_b32_e32 v2, 1
	v_or3_b32 v4, v4, v5, v6
	v_lshlrev_b32_e32 v5, 5, v8
	v_ashrrev_i16_sdwa v1, v2, sext(v1) dst_sel:DWORD dst_unused:UNUSED_PAD src0_sel:DWORD src1_sel:BYTE_0
	v_and_b32_e32 v5, 32, v5
	v_bfe_i32 v11, v1, 0, 16
	v_add_lshl_u32 v1, v5, v11, 1
	v_lshl_add_u32 v130, v4, 12, v1
	v_lshl_add_u32 v132, v3, 12, v1
	v_bfe_i32 v1, v9, 27, 1
	v_lshrrev_b32_e32 v1, 22, v1
	v_add_u32_e32 v1, v0, v1
	v_and_b32_e32 v1, 0xfffffc00, v1
	v_sub_u32_e32 v0, v0, v1
	v_lshrrev_b32_e32 v1, 4, v0
	v_ashrrev_i32_e32 v3, 31, v9
	v_bitop3_b32 v0, v1, v0, 32 bitop3:0x6c
	v_lshrrev_b32_e32 v3, 26, v3
	v_ashrrev_i32_e32 v1, 31, v0
	v_add_u32_e32 v3, v9, v3
	v_lshrrev_b32_e32 v1, 26, v1
	v_ashrrev_i32_e32 v13, 6, v3
	v_add_u32_e32 v1, v0, v1
	v_lshlrev_b32_e32 v3, 3, v13
	v_ashrrev_i32_e32 v12, 6, v1
	v_and_b32_e32 v3, -16, v3
	v_add_u32_e32 v3, v12, v3
	v_and_b32_e32 v4, 3, v12
	s_add_u32 s35, s50, 0x22805000
	v_and_or_b32 v4, v3, s12, v4
	s_mul_hi_i32 s12, s34, 0x38e38e39
	s_addc_u32 s62, s51, 0
	s_lshr_b32 s13, s12, 31
	s_ashr_i32 s12, s12, 6
	s_add_i32 s12, s12, s13
	s_mul_i32 s14, s12, 0xfffffee0
	s_add_i32 s14, s14, s34
	s_ashr_i32 s15, s14, 31
	s_lshr_b32 s15, s15, 29
	s_add_i32 s15, s14, s15
	s_ashr_i32 s16, s4, 6
	s_ashr_i32 s17, s15, 3
	s_and_b32 s15, s15, -8
	s_ashr_i32 s5, s4, 8
	s_lshl_b32 s63, s16, 10
	s_ashr_i32 s13, s12, 31
	s_sub_i32 s14, s14, s15
	s_cmp_lt_i32 s14, 0
	s_cselect_b32 s15, 37, 36
	s_mul_i32 s14, s15, s14
	s_add_i32 s14, s14, s17
	s_ashr_i32 s15, s14, 31
	s_lshr_b32 s15, s15, 26
	s_add_i32 s15, s14, s15
	s_ashr_i32 s17, s15, 6
	s_lshl_b32 s17, s17, 3
	v_and_b32_e32 v1, 0xc0, v1
	s_sub_i32 s18, 36, s17
	v_sub_u32_e32 v0, v0, v1
	s_min_i32 s18, s18, 8
	v_ashrrev_i16_sdwa v0, v2, sext(v0) dst_sel:DWORD dst_unused:UNUSED_PAD src0_sel:DWORD src1_sel:BYTE_0
	s_abs_i32 s19, s18
	v_bfe_i32 v14, v0, 0, 16
	v_cvt_f32_u32_e32 v0, s19
	s_sub_i32 s21, 0, s19
	s_andn2_b32 s15, s15, 63
	s_sub_i32 s14, s14, s15
	v_rcp_iflag_f32_e32 v0, v0
	s_abs_i32 s20, s14
	s_xor_b32 s15, s14, s18
	s_ashr_i32 s15, s15, 31
	v_mul_f32_e32 v0, 0x4f7ffffe, v0
	v_cvt_u32_f32_e32 v0, v0
	v_lshrrev_b32_e32 v5, 2, v3
	v_lshlrev_b32_e32 v6, 1, v3
	v_and_b32_e32 v5, 4, v5
	v_readfirstlane_b32 s22, v0
	s_mul_i32 s21, s21, s22
	s_mul_hi_u32 s21, s22, s21
	s_add_i32 s22, s22, s21
	s_mul_hi_u32 s21, s20, s22
	s_mul_i32 s22, s21, s19
	s_sub_i32 s20, s20, s22
	s_add_i32 s22, s21, 1
	s_sub_i32 s23, s20, s19
	s_cmp_ge_u32 s20, s19
	s_cselect_b32 s21, s22, s21
	s_cselect_b32 s20, s23, s20
	s_add_i32 s22, s21, 1
	s_cmp_ge_u32 s20, s19
	s_cselect_b32 s19, s22, s21
	s_xor_b32 s19, s19, s15
	s_sub_i32 s52, s19, s15
	s_mul_i32 s15, s52, s18
	s_sub_i32 s14, s14, s15
	s_add_i32 s54, s14, s17
	s_ashr_i32 s55, s54, 31
	s_lshl_b64 s[12:13], s[12:13], 12
	s_lshl_b64 s[14:15], s[54:55], 20
	s_add_u32 s17, s35, s14
	s_addc_u32 s18, s62, s15
	s_ashr_i32 s53, s52, 31
	s_lshl_b64 s[14:15], s[52:53], 20
	v_and_b32_e32 v6, 24, v6
	s_add_u32 s14, s10, s14
	v_or3_b32 v4, v4, v5, v6
	v_lshlrev_b32_e32 v5, 5, v13
	s_addc_u32 s15, s11, s15
	v_and_b32_e32 v5, 32, v5
	s_add_u32 s58, s14, s12
	v_add_lshl_u32 v1, v5, v14, 1
	s_addc_u32 s59, s15, s13
	s_add_i32 s53, s63, 0
	v_lshl_add_u32 v134, v4, 12, v1
	s_add_i32 m0, s53, 0x10000
	v_lshl_add_u32 v136, v3, 12, v1
	global_load_lds_dwordx4 v134, s[58:59]
	s_add_i32 m0, s53, 0x12000
	s_add_u32 s14, s58, 0x80000
	global_load_lds_dwordx4 v130, s[58:59]
	s_addc_u32 s15, s59, 0
	s_add_i32 m0, s53, 0x14000
	v_mov_b32_e32 v135, 0
	global_load_lds_dwordx4 v134, s[14:15]
	s_add_i32 m0, s53, 0x16000
	s_add_u32 s56, s17, s12
	s_addc_u32 s57, s18, s13
	s_add_i32 s55, s53, 0x2000
	global_load_lds_dwordx4 v130, s[14:15]
	s_mov_b32 m0, s53
	s_add_u32 s12, s56, 0x80000
	global_load_lds_dwordx4 v136, s[56:57]
	s_mov_b32 m0, s55
	s_addc_u32 s13, s57, 0
	s_add_i32 s64, s53, 0x4000
	global_load_lds_dwordx4 v132, s[56:57]
	s_mov_b32 m0, s64
	s_add_i32 s65, s53, 0x6000
	global_load_lds_dwordx4 v136, s[12:13]
	s_mov_b32 m0, s65
	v_mov_b32_e32 v131, v135
	global_load_lds_dwordx4 v132, s[12:13]
	v_mov_b32_e32 v137, v135
	v_mov_b32_e32 v133, v135
	s_cmp_eq_u32 s5, 1
	s_mov_b32 s66, 0
	v_lshl_add_u64 v[6:7], s[58:59], 0, v[134:135]
	v_lshl_add_u64 v[4:5], s[58:59], 0, v[130:131]
	v_lshl_add_u64 v[2:3], s[56:57], 0, v[136:137]
	v_lshl_add_u64 v[0:1], s[56:57], 0, v[132:133]
	s_cselect_b64 s[12:13], -1, 0
	s_cmp_lg_u32 s5, 1
	s_movk_i32 s67, 0x4000
	s_cbranch_scc1 .LBB0_1400
	s_barrier
.LBB0_1400:
	s_add_u32 s14, s50, 0xdb05000
	s_addc_u32 s15, s51, 0
	s_lshl_b32 s16, s16, 5
	s_and_b32 s21, s16, 0x60
	s_mov_b64 s[16:17], 0x80
	s_add_i32 m0, s53, 0x18000
	v_lshl_add_u64 v[6:7], v[6:7], 0, s[16:17]
	s_lshl_b32 s20, s5, 13
	s_lshl_b32 s22, s21, 7
	s_waitcnt vmcnt(2)
	s_barrier
	global_load_lds_dwordx4 v[6:7], off
	v_lshl_add_u64 v[4:5], v[4:5], 0, s[16:17]
	s_add_i32 m0, s53, 0x1a000
	s_add_i32 s68, s53, 0x8000
	s_add_i32 s69, s53, 0xa000
	global_load_lds_dwordx4 v[4:5], off
	v_lshl_add_u64 v[2:3], v[2:3], 0, s[16:17]
	s_mov_b32 m0, s68
	s_add_u32 s18, s58, 0x80080
	global_load_lds_dwordx4 v[2:3], off
	v_lshl_add_u64 v[0:1], v[0:1], 0, s[16:17]
	s_mov_b32 m0, s69
	s_addc_u32 s19, s59, 0
	global_load_lds_dwordx4 v[0:1], off
	s_add_i32 m0, s53, 0x1c000
	v_lshl_add_u64 v[0:1], s[18:19], 0, v[134:135]
	global_load_lds_dwordx4 v[0:1], off
	v_lshl_add_u64 v[0:1], s[18:19], 0, v[130:131]
	s_add_i32 m0, s53, 0x1e000
	s_cmpk_lt_u32 s4, 0x100
	global_load_lds_dwordx4 v[0:1], off
	v_lshrrev_b32_e32 v1, 1, v9
	v_and_b32_e32 v1, 24, v1
	v_and_b32_e32 v0, 15, v9
	v_lshlrev_b32_e32 v2, 1, v1
	v_lshl_or_b32 v129, s5, 6, v0
	v_lshl_or_b32 v0, v0, 6, v2
	v_lshlrev_b32_e32 v2, 2, v9
	v_and_b32_e32 v2, 32, v2
	v_bitop3_b32 v3, v0, s20, v2 bitop3:0xde
	v_bitop3_b32 v154, v0, s22, v2 bitop3:0xde
	v_lshlrev_b32_e32 v0, 15, v13
	v_and_b32_e32 v0, 0xffff0000, v0
	v_or_b32_e32 v155, s21, v1
	v_lshl_add_u32 v0, v12, 12, v0
	v_and_b32_e32 v1, 1, v13
	v_lshl_or_b32 v0, v1, 6, v0
	v_lshl_add_u32 v138, v14, 1, v0
	v_lshlrev_b32_e32 v0, 15, v8
	v_and_b32_e32 v0, 0xffff0000, v0
	s_waitcnt vmcnt(6)
	v_lshl_add_u32 v0, v10, 12, v0
	v_and_b32_e32 v1, 1, v8
	s_cselect_b64 s[18:19], -1, 0
	v_lshl_or_b32 v0, v1, 6, v0
	s_add_i32 s72, 0, 0x10000
	s_add_i32 s73, 0, 0x14000
	s_ashr_i32 s70, s94, 31
	s_mov_b32 s71, s94
	s_cmp_lg_u32 s94, 0x100
	s_cbranch_scc1 .Lpapr_stride_done
	s_cmp_lt_u32 s34, 64
	s_cbranch_scc0 .Lpapr_stride_done
	s_movk_i32 s71, 0xe0
	s_cmp_lt_u32 s34, 32
	s_cbranch_scc0 .Lpapr_stride_done
	s_movk_i32 s71, 0x120
.Lpapr_stride_done:
	v_mov_b32_e32 v139, v135
	v_lshl_add_u32 v140, v11, 1, v0
	v_mov_b32_e32 v141, v135
	v_mov_b64_e32 v[142:143], 0x120
	v_mov_b64_e32 v[144:145], 0x11f
	v_add_u32_e32 v156, s72, v154
	v_add_u32_e32 v157, s73, v154
	v_add_u32_e32 v158, 0, v3
	s_movk_i32 s74, 0x5c00
	s_mov_b64 s[20:21], 0x4c00
	s_barrier
	s_branch .LBB0_1403

.LBB0_1409:
	s_cmp_lg_u32 s94, 0x100
	s_cbranch_scc1 .Lpapr_nowait
	s_cmp_lt_u32 s34, 32
	s_cbranch_scc1 .Lpapr_nowait
	s_cmp_ge_u32 s34, 64
	s_cbranch_scc1 .Lpapr_nowait
	s_cmp_lg_u32 s66, 2
	s_cbranch_scc1 .Lpapr_nowait
	s_sub_u32 s84, s34, 32
	s_lshl_b32 s84, s84, 2
	v_mov_b32_e32 v252, s84
.Lpapr_poll:
	global_load_dword v253, v252, s[50:51] sc1
	s_waitcnt vmcnt(0)
	v_readfirstlane_b32 s85, v253
	s_cmp_lg_u32 s85, 0
	s_cbranch_scc1 .Lpapr_got
	s_sleep 1
	s_branch .Lpapr_poll
.Lpapr_got:
	buffer_inv sc1
	s_waitcnt vmcnt(0)

.LBB0_1413:
	s_abs_i32 s4, s94
	v_cvt_f32_u32_e32 v0, s4
	s_sub_i32 s5, 0, s4
	v_rcp_iflag_f32_e32 v0, v0
	s_nop 0
	v_mul_f32_e32 v0, 0x4f7ffffe, v0
	v_cvt_u32_f32_e32 v0, v0
	s_nop 0
	v_readfirstlane_b32 s6, v0
	s_mul_i32 s5, s5, s6
	s_mul_hi_u32 s5, s6, s5
	s_add_i32 s6, s6, s5
	s_mul_hi_u32 s5, s6, 0x120
	s_mul_i32 s5, s5, s4
	s_sub_i32 s5, 0x120, s5
	s_sub_i32 s6, s5, s4
	s_cmp_ge_u32 s5, s4
	s_cselect_b32 s5, s6, s5
	s_sub_i32 s6, s5, s4
	s_cmp_ge_u32 s5, s4
	s_cselect_b32 s6, s6, s5
	s_cmp_lg_u32 s94, 0x100
	s_cbranch_scc1 .Lpapr_rem_done
	s_movk_i32 s6, 64
.Lpapr_rem_done:
	s_cmp_lg_u32 s6, 0
	s_cbranch_scc0 .LBB0_1486
	s_cmp_lt_i32 s34, s6
	s_cbranch_scc1 .LBB0_1485
	v_lshrrev_b32_e32 v0, 6, v128
	s_sub_i32 s4, s34, s6
	v_lshl_add_u32 v5, s4, 3, v0
	s_movk_i32 s4, 0x1600
	v_cmp_gt_i32_e32 vcc, s4, v5
	s_and_saveexec_b64 s[4:5], vcc
	s_cbranch_execz .LBB0_1484
	s_sub_i32 s6, s94, s6
	s_lshl_b32 s33, s6, 3
	s_movk_i32 s6, 0x2200
	v_mad_u32_u24 v1, v0, s6, 0
	s_add_u32 s6, s50, 0x8404000
	s_addc_u32 s7, s51, 0
	s_add_u32 s8, s50, 0x7c04000
	s_addc_u32 s9, s51, 0
	s_add_u32 s12, s50, 0x4204000
	s_addc_u32 s13, s51, 0
	s_add_u32 s14, s50, 0x2c04000
	s_addc_u32 s15, s51, 0
	s_add_u32 s16, s50, 0x4000
	s_waitcnt vmcnt(0)
	v_lshlrev_b32_e32 v2, 3, v128
	s_addc_u32 s17, s51, 0
	v_bfe_u32 v9, v128, 3, 3
	v_and_b32_e32 v2, 56, v2
	s_add_u32 s18, s50, 0xb004000
	v_bfe_u32 v4, v128, 5, 1
	v_and_b32_e32 v0, 31, v128
	v_mul_u32_u24_e32 v3, 0x84, v2
	v_lshlrev_b32_e32 v6, 2, v9
	s_addc_u32 s19, s51, 0
	v_mov_b32_e32 v7, 0
	v_lshl_add_u32 v8, v0, 2, v1
	s_movk_i32 s35, 0x84
	v_add3_u32 v20, v1, v3, v6
	v_or_b32_e32 v21, 8, v9
	v_or_b32_e32 v22, 16, v9
	v_or_b32_e32 v23, 24, v9
	v_mov_b32_e32 v1, v4
	s_mov_b64 s[20:21], 0
	s_movk_i32 s54, 0xf7ff
	s_movk_i32 s55, 0xfc00
	v_lshlrev_b32_e32 v6, 2, v0
	v_lshlrev_b32_e32 v10, 1, v2
	s_movk_i32 s56, 0x15ff
